# k08 + every GEMM K-loop header padded to a 64-byte boundary (code placement)
# speedup vs baseline: 1.0030x; 1.0030x over previous
.LBB0_201:
	s_and_b32 s99, s45, 1
	s_lshl_b32 s99, s99, 12
	v_readfirstlane_b32 s100, v0
	s_and_b32 s100, s100, 0xc0
	s_lshl_b32 s100, s100, 4
	s_add_i32 s99, s99, s100
	s_add_i32 m0, s99, 0x21000
	s_lshl_b32 s99, s26, 12
	s_add_u32 s100, s76, s99
	s_addc_u32 s101, s77, 0
	v_and_b32_e32 v129, 0xff, v0
	v_lshlrev_b32_e32 v129, 4, v129
	global_load_lds_dwordx4 v129, s[100:101]
	s_ashr_i32 s21, s20, 31
	s_lshl_b64 s[0:1], s[20:21], 19
	s_add_u32 s22, s78, s0
	s_addc_u32 s23, s79, s1
	s_and_b64 s[0:1], s[4:5], exec
	s_cselect_b32 s21, s23, s29
	s_cselect_b32 s47, s22, s28
	s_ashr_i32 s19, s18, 31
	s_lshl_b64 s[0:1], s[18:19], 19
	s_add_u32 s24, s34, s0
	s_addc_u32 s25, s35, s1
	s_and_b64 s[0:1], s[4:5], exec
	s_cselect_b32 s19, s25, s3
	s_cselect_b32 s48, s24, s2
	s_add_u32 s28, s28, 0x40080
	s_addc_u32 s29, s29, 0
	s_add_u32 s49, s2, 0x100
	v_mov_b32_e32 v2, 0
	s_addc_u32 s50, s3, 0
	s_mov_b32 s51, -2
	v_mov_b32_e32 v3, v2
	v_mov_b32_e32 v4, v2
	v_mov_b32_e32 v5, v2
	v_mov_b32_e32 v6, v2
	v_mov_b32_e32 v7, v2
	v_mov_b32_e32 v8, v2
	v_mov_b32_e32 v9, v2
	v_mov_b32_e32 v18, v2
	v_mov_b32_e32 v19, v2
	v_mov_b32_e32 v20, v2
	v_mov_b32_e32 v21, v2
	v_mov_b32_e32 v22, v2
	v_mov_b32_e32 v23, v2
	v_mov_b32_e32 v24, v2
	v_mov_b32_e32 v25, v2
	v_mov_b32_e32 v34, v2
	v_mov_b32_e32 v35, v2
	v_mov_b32_e32 v36, v2
	v_mov_b32_e32 v37, v2
	v_mov_b32_e32 v38, v2
	v_mov_b32_e32 v39, v2
	v_mov_b32_e32 v40, v2
	v_mov_b32_e32 v41, v2
	v_mov_b32_e32 v50, v2
	v_mov_b32_e32 v51, v2
	v_mov_b32_e32 v52, v2
	v_mov_b32_e32 v53, v2
	v_mov_b32_e32 v54, v2
	v_mov_b32_e32 v55, v2
	v_mov_b32_e32 v56, v2
	v_mov_b32_e32 v57, v2
	v_mov_b32_e32 v10, v2
	v_mov_b32_e32 v11, v2
	v_mov_b32_e32 v12, v2
	v_mov_b32_e32 v13, v2
	v_mov_b32_e32 v14, v2
	v_mov_b32_e32 v15, v2
	v_mov_b32_e32 v16, v2
	v_mov_b32_e32 v17, v2
	v_mov_b32_e32 v26, v2
	v_mov_b32_e32 v27, v2
	v_mov_b32_e32 v28, v2
	v_mov_b32_e32 v29, v2
	v_mov_b32_e32 v30, v2
	v_mov_b32_e32 v31, v2
	v_mov_b32_e32 v32, v2
	v_mov_b32_e32 v33, v2
	v_mov_b32_e32 v42, v2
	v_mov_b32_e32 v43, v2
	v_mov_b32_e32 v44, v2
	v_mov_b32_e32 v45, v2
	v_mov_b32_e32 v46, v2
	v_mov_b32_e32 v47, v2
	v_mov_b32_e32 v48, v2
	v_mov_b32_e32 v49, v2
	v_mov_b32_e32 v58, v2
	v_mov_b32_e32 v59, v2
	v_mov_b32_e32 v60, v2
	v_mov_b32_e32 v61, v2
	v_mov_b32_e32 v62, v2
	v_mov_b32_e32 v63, v2
	v_mov_b32_e32 v64, v2
	v_mov_b32_e32 v65, v2
	v_mov_b32_e32 v66, v2
	v_mov_b32_e32 v67, v2
	v_mov_b32_e32 v68, v2
	v_mov_b32_e32 v69, v2
	v_mov_b32_e32 v70, v2
	v_mov_b32_e32 v71, v2
	v_mov_b32_e32 v72, v2
	v_mov_b32_e32 v73, v2
	v_mov_b32_e32 v82, v2
	v_mov_b32_e32 v83, v2
	v_mov_b32_e32 v84, v2
	v_mov_b32_e32 v85, v2
	v_mov_b32_e32 v86, v2
	v_mov_b32_e32 v87, v2
	v_mov_b32_e32 v88, v2
	v_mov_b32_e32 v89, v2
	v_mov_b32_e32 v98, v2
	v_mov_b32_e32 v99, v2
	v_mov_b32_e32 v100, v2
	v_mov_b32_e32 v101, v2
	v_mov_b32_e32 v102, v2
	v_mov_b32_e32 v103, v2
	v_mov_b32_e32 v104, v2
	v_mov_b32_e32 v105, v2
	v_mov_b32_e32 v114, v2
	v_mov_b32_e32 v115, v2
	v_mov_b32_e32 v116, v2
	v_mov_b32_e32 v117, v2
	v_mov_b32_e32 v122, v2
	v_mov_b32_e32 v123, v2
	v_mov_b32_e32 v124, v2
	v_mov_b32_e32 v125, v2
	v_mov_b32_e32 v74, v2
	v_mov_b32_e32 v75, v2
	v_mov_b32_e32 v76, v2
	v_mov_b32_e32 v77, v2
	v_mov_b32_e32 v78, v2
	v_mov_b32_e32 v79, v2
	v_mov_b32_e32 v80, v2
	v_mov_b32_e32 v81, v2
	v_mov_b32_e32 v90, v2
	v_mov_b32_e32 v91, v2
	v_mov_b32_e32 v92, v2
	v_mov_b32_e32 v93, v2
	v_mov_b32_e32 v94, v2
	v_mov_b32_e32 v95, v2
	v_mov_b32_e32 v96, v2
	v_mov_b32_e32 v97, v2
	v_mov_b32_e32 v106, v2
	v_mov_b32_e32 v107, v2
	v_mov_b32_e32 v108, v2
	v_mov_b32_e32 v109, v2
	v_mov_b32_e32 v110, v2
	v_mov_b32_e32 v111, v2
	v_mov_b32_e32 v112, v2
	v_mov_b32_e32 v113, v2
	v_mov_b32_e32 v118, v2
	v_mov_b32_e32 v119, v2
	v_mov_b32_e32 v120, v2
	v_mov_b32_e32 v121, v2
	v_mov_b32_e32 v126, v2
	v_mov_b32_e32 v127, v2
	v_mov_b32_e32 v128, v2
	v_mov_b32_e32 v129, v2
	s_nop 0
	s_nop 0
	s_nop 0

.LBB0_282:
	s_ashr_i32 s29, s28, 31
	s_lshl_b64 s[0:1], s[28:29], 19
	s_add_u32 s30, s78, s0
	s_addc_u32 s31, s79, s1
	s_and_b64 s[0:1], s[4:5], exec
	s_cselect_b32 s7, s31, s11
	s_cselect_b32 s9, s30, s10
	s_ashr_i32 s27, s26, 31
	s_lshl_b64 s[0:1], s[26:27], 19
	s_add_u32 s34, s33, s0
	s_addc_u32 s35, s38, s1
	s_and_b64 s[0:1], s[4:5], exec
	s_cselect_b32 s27, s35, s3
	s_cselect_b32 s29, s34, s2
	s_add_u32 s10, s10, 0x40080
	s_addc_u32 s11, s11, 0
	s_add_u32 s36, s2, 0x100
	v_mov_b32_e32 v2, 0
	s_addc_u32 s37, s3, 0
	s_mov_b32 s51, -2
	v_mov_b32_e32 v3, v2
	v_mov_b32_e32 v4, v2
	v_mov_b32_e32 v5, v2
	v_mov_b32_e32 v6, v2
	v_mov_b32_e32 v7, v2
	v_mov_b32_e32 v8, v2
	v_mov_b32_e32 v9, v2
	v_mov_b32_e32 v10, v2
	v_mov_b32_e32 v11, v2
	v_mov_b32_e32 v12, v2
	v_mov_b32_e32 v13, v2
	v_mov_b32_e32 v14, v2
	v_mov_b32_e32 v15, v2
	v_mov_b32_e32 v16, v2
	v_mov_b32_e32 v17, v2
	v_mov_b32_e32 v18, v2
	v_mov_b32_e32 v19, v2
	v_mov_b32_e32 v20, v2
	v_mov_b32_e32 v21, v2
	v_mov_b32_e32 v22, v2
	v_mov_b32_e32 v23, v2
	v_mov_b32_e32 v24, v2
	v_mov_b32_e32 v25, v2
	v_mov_b32_e32 v26, v2
	v_mov_b32_e32 v27, v2
	v_mov_b32_e32 v28, v2
	v_mov_b32_e32 v29, v2
	v_mov_b32_e32 v30, v2
	v_mov_b32_e32 v31, v2
	v_mov_b32_e32 v32, v2
	v_mov_b32_e32 v33, v2
	v_mov_b32_e32 v66, v2
	v_mov_b32_e32 v67, v2
	v_mov_b32_e32 v68, v2
	v_mov_b32_e32 v69, v2
	v_mov_b32_e32 v70, v2
	v_mov_b32_e32 v71, v2
	v_mov_b32_e32 v72, v2
	v_mov_b32_e32 v73, v2
	v_mov_b32_e32 v74, v2
	v_mov_b32_e32 v75, v2
	v_mov_b32_e32 v76, v2
	v_mov_b32_e32 v77, v2
	v_mov_b32_e32 v78, v2
	v_mov_b32_e32 v79, v2
	v_mov_b32_e32 v80, v2
	v_mov_b32_e32 v81, v2
	v_mov_b32_e32 v82, v2
	v_mov_b32_e32 v83, v2
	v_mov_b32_e32 v84, v2
	v_mov_b32_e32 v85, v2
	v_mov_b32_e32 v86, v2
	v_mov_b32_e32 v87, v2
	v_mov_b32_e32 v88, v2
	v_mov_b32_e32 v89, v2
	v_mov_b32_e32 v90, v2
	v_mov_b32_e32 v91, v2
	v_mov_b32_e32 v92, v2
	v_mov_b32_e32 v93, v2
	v_mov_b32_e32 v94, v2
	v_mov_b32_e32 v95, v2
	v_mov_b32_e32 v96, v2
	v_mov_b32_e32 v97, v2
	v_mov_b32_e32 v34, v2
	v_mov_b32_e32 v35, v2
	v_mov_b32_e32 v36, v2
	v_mov_b32_e32 v37, v2
	v_mov_b32_e32 v38, v2
	v_mov_b32_e32 v39, v2
	v_mov_b32_e32 v40, v2
	v_mov_b32_e32 v41, v2
	v_mov_b32_e32 v42, v2
	v_mov_b32_e32 v43, v2
	v_mov_b32_e32 v44, v2
	v_mov_b32_e32 v45, v2
	v_mov_b32_e32 v46, v2
	v_mov_b32_e32 v47, v2
	v_mov_b32_e32 v48, v2
	v_mov_b32_e32 v49, v2
	v_mov_b32_e32 v50, v2
	v_mov_b32_e32 v51, v2
	v_mov_b32_e32 v52, v2
	v_mov_b32_e32 v53, v2
	v_mov_b32_e32 v54, v2
	v_mov_b32_e32 v55, v2
	v_mov_b32_e32 v56, v2
	v_mov_b32_e32 v57, v2
	v_mov_b32_e32 v58, v2
	v_mov_b32_e32 v59, v2
	v_mov_b32_e32 v60, v2
	v_mov_b32_e32 v61, v2
	v_mov_b32_e32 v62, v2
	v_mov_b32_e32 v63, v2
	v_mov_b32_e32 v64, v2
	v_mov_b32_e32 v65, v2
	v_mov_b32_e32 v98, v2
	v_mov_b32_e32 v99, v2
	v_mov_b32_e32 v100, v2
	v_mov_b32_e32 v101, v2
	v_mov_b32_e32 v102, v2
	v_mov_b32_e32 v103, v2
	v_mov_b32_e32 v104, v2
	v_mov_b32_e32 v105, v2
	v_mov_b32_e32 v106, v2
	v_mov_b32_e32 v107, v2
	v_mov_b32_e32 v108, v2
	v_mov_b32_e32 v109, v2
	v_mov_b32_e32 v110, v2
	v_mov_b32_e32 v111, v2
	v_mov_b32_e32 v112, v2
	v_mov_b32_e32 v113, v2
	v_mov_b32_e32 v130, v2
	v_mov_b32_e32 v131, v2
	v_mov_b32_e32 v132, v2
	v_mov_b32_e32 v133, v2
	v_mov_b32_e32 v134, v2
	v_mov_b32_e32 v135, v2
	v_mov_b32_e32 v136, v2
	v_mov_b32_e32 v137, v2
	v_mov_b32_e32 v138, v2
	v_mov_b32_e32 v139, v2
	v_mov_b32_e32 v140, v2
	v_mov_b32_e32 v141, v2
	v_mov_b32_e32 v142, v2
	v_mov_b32_e32 v143, v2
	v_mov_b32_e32 v144, v2
	v_mov_b32_e32 v145, v2
	s_nop 0
	s_nop 0
	s_nop 0
	s_nop 0
	s_nop 0
	s_nop 0
	s_nop 0
	s_nop 0
	s_nop 0
	s_nop 0
	s_nop 0
	s_nop 0
	s_nop 0
	s_nop 0

.LBB0_381:
	s_ashr_i32 s21, s20, 31
	s_lshl_b64 s[0:1], s[20:21], 19
	s_add_u32 s22, s33, s0
	s_addc_u32 s23, s34, s1
	s_and_b64 s[0:1], s[6:7], exec
	s_cselect_b32 s11, s23, s29
	s_cselect_b32 s21, s22, s28
	s_ashr_i32 s19, s18, 31
	s_lshl_b64 s[0:1], s[18:19], 19
	s_add_u32 s24, s35, s0
	s_addc_u32 s25, s36, s1
	s_and_b64 s[0:1], s[6:7], exec
	s_cselect_b32 s19, s25, s3
	s_cselect_b32 s48, s24, s2
	s_add_u32 s28, s28, 0x40080
	s_addc_u32 s29, s29, 0
	s_add_u32 s49, s2, 0x100
	v_mov_b32_e32 v2, 0
	s_addc_u32 s50, s3, 0
	s_mov_b32 s51, -2
	s_waitcnt lgkmcnt(0)
	v_mov_b32_e32 v3, v2
	v_mov_b32_e32 v4, v2
	v_mov_b32_e32 v5, v2
	v_mov_b32_e32 v6, v2
	v_mov_b32_e32 v7, v2
	v_mov_b32_e32 v8, v2
	v_mov_b32_e32 v9, v2
	v_mov_b32_e32 v18, v2
	v_mov_b32_e32 v19, v2
	v_mov_b32_e32 v20, v2
	v_mov_b32_e32 v21, v2
	v_mov_b32_e32 v22, v2
	v_mov_b32_e32 v23, v2
	v_mov_b32_e32 v24, v2
	v_mov_b32_e32 v25, v2
	v_mov_b32_e32 v34, v2
	v_mov_b32_e32 v35, v2
	v_mov_b32_e32 v36, v2
	v_mov_b32_e32 v37, v2
	v_mov_b32_e32 v38, v2
	v_mov_b32_e32 v39, v2
	v_mov_b32_e32 v40, v2
	v_mov_b32_e32 v41, v2
	v_mov_b32_e32 v50, v2
	v_mov_b32_e32 v51, v2
	v_mov_b32_e32 v52, v2
	v_mov_b32_e32 v53, v2
	v_mov_b32_e32 v54, v2
	v_mov_b32_e32 v55, v2
	v_mov_b32_e32 v56, v2
	v_mov_b32_e32 v57, v2
	v_mov_b32_e32 v10, v2
	v_mov_b32_e32 v11, v2
	v_mov_b32_e32 v12, v2
	v_mov_b32_e32 v13, v2
	v_mov_b32_e32 v14, v2
	v_mov_b32_e32 v15, v2
	v_mov_b32_e32 v16, v2
	v_mov_b32_e32 v17, v2
	v_mov_b32_e32 v26, v2
	v_mov_b32_e32 v27, v2
	v_mov_b32_e32 v28, v2
	v_mov_b32_e32 v29, v2
	v_mov_b32_e32 v30, v2
	v_mov_b32_e32 v31, v2
	v_mov_b32_e32 v32, v2
	v_mov_b32_e32 v33, v2
	v_mov_b32_e32 v42, v2
	v_mov_b32_e32 v43, v2
	v_mov_b32_e32 v44, v2
	v_mov_b32_e32 v45, v2
	v_mov_b32_e32 v46, v2
	v_mov_b32_e32 v47, v2
	v_mov_b32_e32 v48, v2
	v_mov_b32_e32 v49, v2
	v_mov_b32_e32 v58, v2
	v_mov_b32_e32 v59, v2
	v_mov_b32_e32 v60, v2
	v_mov_b32_e32 v61, v2
	v_mov_b32_e32 v62, v2
	v_mov_b32_e32 v63, v2
	v_mov_b32_e32 v64, v2
	v_mov_b32_e32 v65, v2
	v_mov_b32_e32 v66, v2
	v_mov_b32_e32 v67, v2
	v_mov_b32_e32 v68, v2
	v_mov_b32_e32 v69, v2
	v_mov_b32_e32 v70, v2
	v_mov_b32_e32 v71, v2
	v_mov_b32_e32 v72, v2
	v_mov_b32_e32 v73, v2
	v_mov_b32_e32 v82, v2
	v_mov_b32_e32 v83, v2
	v_mov_b32_e32 v84, v2
	v_mov_b32_e32 v85, v2
	v_mov_b32_e32 v86, v2
	v_mov_b32_e32 v87, v2
	v_mov_b32_e32 v88, v2
	v_mov_b32_e32 v89, v2
	v_mov_b32_e32 v98, v2
	v_mov_b32_e32 v99, v2
	v_mov_b32_e32 v100, v2
	v_mov_b32_e32 v101, v2
	v_mov_b32_e32 v102, v2
	v_mov_b32_e32 v103, v2
	v_mov_b32_e32 v104, v2
	v_mov_b32_e32 v105, v2
	v_mov_b32_e32 v114, v2
	v_mov_b32_e32 v115, v2
	v_mov_b32_e32 v116, v2
	v_mov_b32_e32 v117, v2
	v_mov_b32_e32 v118, v2
	v_mov_b32_e32 v119, v2
	v_mov_b32_e32 v120, v2
	v_mov_b32_e32 v121, v2
	v_mov_b32_e32 v74, v2
	v_mov_b32_e32 v75, v2
	v_mov_b32_e32 v76, v2
	v_mov_b32_e32 v77, v2
	v_mov_b32_e32 v78, v2
	v_mov_b32_e32 v79, v2
	v_mov_b32_e32 v80, v2
	v_mov_b32_e32 v81, v2
	v_mov_b32_e32 v90, v2
	v_mov_b32_e32 v91, v2
	v_mov_b32_e32 v92, v2
	v_mov_b32_e32 v93, v2
	v_mov_b32_e32 v94, v2
	v_mov_b32_e32 v95, v2
	v_mov_b32_e32 v96, v2
	v_mov_b32_e32 v97, v2
	v_mov_b32_e32 v106, v2
	v_mov_b32_e32 v107, v2
	v_mov_b32_e32 v108, v2
	v_mov_b32_e32 v109, v2
	v_mov_b32_e32 v110, v2
	v_mov_b32_e32 v111, v2
	v_mov_b32_e32 v112, v2
	v_mov_b32_e32 v113, v2
	v_mov_b32_e32 v122, v2
	v_mov_b32_e32 v123, v2
	v_mov_b32_e32 v124, v2
	v_mov_b32_e32 v125, v2
	v_mov_b32_e32 v126, v2
	v_mov_b32_e32 v127, v2
	v_mov_b32_e32 v128, v2
	v_mov_b32_e32 v129, v2
	s_nop 0
	s_nop 0
	s_nop 0
	s_nop 0
	s_nop 0
	s_nop 0
	s_nop 0
	s_nop 0
	s_nop 0
	s_nop 0

.LBB0_470:
	s_and_b32 s99, s48, 1
	s_lshl_b32 s99, s99, 12
	v_readfirstlane_b32 s100, v0
	s_and_b32 s100, s100, 0xc0
	s_lshl_b32 s100, s100, 4
	s_add_i32 s99, s99, s100
	s_add_i32 m0, s99, 0x21000
	s_lshl_b32 s99, s26, 12
	s_add_u32 s100, s76, s99
	s_addc_u32 s101, s77, 0
	v_and_b32_e32 v129, 0xff, v0
	v_lshlrev_b32_e32 v129, 4, v129
	global_load_lds_dwordx4 v129, s[100:101]
	s_ashr_i32 s21, s20, 31
	s_lshl_b64 s[0:1], s[20:21], 19
	s_add_u32 s22, s78, s0
	s_addc_u32 s23, s79, s1
	s_and_b64 s[0:1], s[4:5], exec
	s_cselect_b32 s21, s23, s29
	s_cselect_b32 s49, s22, s28
	s_ashr_i32 s19, s18, 31
	s_lshl_b64 s[0:1], s[18:19], 19
	s_add_u32 s24, s33, s0
	s_addc_u32 s25, s34, s1
	s_and_b64 s[0:1], s[4:5], exec
	s_cselect_b32 s19, s25, s3
	s_cselect_b32 s50, s24, s2
	s_add_u32 s28, s28, 0x40080
	s_addc_u32 s29, s29, 0
	s_add_u32 s51, s2, 0x100
	v_mov_b32_e32 v2, 0
	s_addc_u32 s52, s3, 0
	s_mov_b32 s53, -2
	v_mov_b32_e32 v3, v2
	v_mov_b32_e32 v4, v2
	v_mov_b32_e32 v5, v2
	v_mov_b32_e32 v10, v2
	v_mov_b32_e32 v11, v2
	v_mov_b32_e32 v12, v2
	v_mov_b32_e32 v13, v2
	v_mov_b32_e32 v18, v2
	v_mov_b32_e32 v19, v2
	v_mov_b32_e32 v20, v2
	v_mov_b32_e32 v21, v2
	v_mov_b32_e32 v26, v2
	v_mov_b32_e32 v27, v2
	v_mov_b32_e32 v28, v2
	v_mov_b32_e32 v29, v2
	v_mov_b32_e32 v34, v2
	v_mov_b32_e32 v35, v2
	v_mov_b32_e32 v36, v2
	v_mov_b32_e32 v37, v2
	v_mov_b32_e32 v42, v2
	v_mov_b32_e32 v43, v2
	v_mov_b32_e32 v44, v2
	v_mov_b32_e32 v45, v2
	v_mov_b32_e32 v50, v2
	v_mov_b32_e32 v51, v2
	v_mov_b32_e32 v52, v2
	v_mov_b32_e32 v53, v2
	v_mov_b32_e32 v58, v2
	v_mov_b32_e32 v59, v2
	v_mov_b32_e32 v60, v2
	v_mov_b32_e32 v61, v2
	v_mov_b32_e32 v6, v2
	v_mov_b32_e32 v7, v2
	v_mov_b32_e32 v8, v2
	v_mov_b32_e32 v9, v2
	v_mov_b32_e32 v14, v2
	v_mov_b32_e32 v15, v2
	v_mov_b32_e32 v16, v2
	v_mov_b32_e32 v17, v2
	v_mov_b32_e32 v22, v2
	v_mov_b32_e32 v23, v2
	v_mov_b32_e32 v24, v2
	v_mov_b32_e32 v25, v2
	v_mov_b32_e32 v30, v2
	v_mov_b32_e32 v31, v2
	v_mov_b32_e32 v32, v2
	v_mov_b32_e32 v33, v2
	v_mov_b32_e32 v38, v2
	v_mov_b32_e32 v39, v2
	v_mov_b32_e32 v40, v2
	v_mov_b32_e32 v41, v2
	v_mov_b32_e32 v46, v2
	v_mov_b32_e32 v47, v2
	v_mov_b32_e32 v48, v2
	v_mov_b32_e32 v49, v2
	v_mov_b32_e32 v54, v2
	v_mov_b32_e32 v55, v2
	v_mov_b32_e32 v56, v2
	v_mov_b32_e32 v57, v2
	v_mov_b32_e32 v62, v2
	v_mov_b32_e32 v63, v2
	v_mov_b32_e32 v64, v2
	v_mov_b32_e32 v65, v2
	v_mov_b32_e32 v66, v2
	v_mov_b32_e32 v67, v2
	v_mov_b32_e32 v68, v2
	v_mov_b32_e32 v69, v2
	v_mov_b32_e32 v74, v2
	v_mov_b32_e32 v75, v2
	v_mov_b32_e32 v76, v2
	v_mov_b32_e32 v77, v2
	v_mov_b32_e32 v82, v2
	v_mov_b32_e32 v83, v2
	v_mov_b32_e32 v84, v2
	v_mov_b32_e32 v85, v2
	v_mov_b32_e32 v90, v2
	v_mov_b32_e32 v91, v2
	v_mov_b32_e32 v92, v2
	v_mov_b32_e32 v93, v2
	v_mov_b32_e32 v98, v2
	v_mov_b32_e32 v99, v2
	v_mov_b32_e32 v100, v2
	v_mov_b32_e32 v101, v2
	v_mov_b32_e32 v106, v2
	v_mov_b32_e32 v107, v2
	v_mov_b32_e32 v108, v2
	v_mov_b32_e32 v109, v2
	v_mov_b32_e32 v114, v2
	v_mov_b32_e32 v115, v2
	v_mov_b32_e32 v116, v2
	v_mov_b32_e32 v117, v2
	v_mov_b32_e32 v122, v2
	v_mov_b32_e32 v123, v2
	v_mov_b32_e32 v124, v2
	v_mov_b32_e32 v125, v2
	v_mov_b32_e32 v70, v2
	v_mov_b32_e32 v71, v2
	v_mov_b32_e32 v72, v2
	v_mov_b32_e32 v73, v2
	v_mov_b32_e32 v78, v2
	v_mov_b32_e32 v79, v2
	v_mov_b32_e32 v80, v2
	v_mov_b32_e32 v81, v2
	v_mov_b32_e32 v86, v2
	v_mov_b32_e32 v87, v2
	v_mov_b32_e32 v88, v2
	v_mov_b32_e32 v89, v2
	v_mov_b32_e32 v94, v2
	v_mov_b32_e32 v95, v2
	v_mov_b32_e32 v96, v2
	v_mov_b32_e32 v97, v2
	v_mov_b32_e32 v102, v2
	v_mov_b32_e32 v103, v2
	v_mov_b32_e32 v104, v2
	v_mov_b32_e32 v105, v2
	v_mov_b32_e32 v110, v2
	v_mov_b32_e32 v111, v2
	v_mov_b32_e32 v112, v2
	v_mov_b32_e32 v113, v2
	v_mov_b32_e32 v118, v2
	v_mov_b32_e32 v119, v2
	v_mov_b32_e32 v120, v2
	v_mov_b32_e32 v121, v2
	v_mov_b32_e32 v126, v2
	v_mov_b32_e32 v127, v2
	v_mov_b32_e32 v128, v2
	v_mov_b32_e32 v129, v2
	s_nop 0
	s_nop 0
	s_nop 0
	s_nop 0
	s_nop 0
	s_nop 0
	s_nop 0
	s_nop 0
	s_nop 0
	s_nop 0
	s_nop 0

.LBB0_583:
	s_add_u32 s22, s22, 0xb0080
	s_addc_u32 s23, s23, 0
	s_add_u32 s45, s2, 0x100
	v_mov_b32_e32 v2, 0
	s_addc_u32 s46, s3, 0
	s_mov_b32 s47, -2
	s_waitcnt lgkmcnt(0)
	v_mov_b32_e32 v3, v2
	v_mov_b32_e32 v4, v2
	v_mov_b32_e32 v5, v2
	v_mov_b32_e32 v6, v2
	v_mov_b32_e32 v7, v2
	v_mov_b32_e32 v8, v2
	v_mov_b32_e32 v9, v2
	v_mov_b32_e32 v18, v2
	v_mov_b32_e32 v19, v2
	v_mov_b32_e32 v20, v2
	v_mov_b32_e32 v21, v2
	v_mov_b32_e32 v22, v2
	v_mov_b32_e32 v23, v2
	v_mov_b32_e32 v24, v2
	v_mov_b32_e32 v25, v2
	v_mov_b32_e32 v34, v2
	v_mov_b32_e32 v35, v2
	v_mov_b32_e32 v36, v2
	v_mov_b32_e32 v37, v2
	v_mov_b32_e32 v38, v2
	v_mov_b32_e32 v39, v2
	v_mov_b32_e32 v40, v2
	v_mov_b32_e32 v41, v2
	v_mov_b32_e32 v50, v2
	v_mov_b32_e32 v51, v2
	v_mov_b32_e32 v52, v2
	v_mov_b32_e32 v53, v2
	v_mov_b32_e32 v54, v2
	v_mov_b32_e32 v55, v2
	v_mov_b32_e32 v56, v2
	v_mov_b32_e32 v57, v2
	v_mov_b32_e32 v10, v2
	v_mov_b32_e32 v11, v2
	v_mov_b32_e32 v12, v2
	v_mov_b32_e32 v13, v2
	v_mov_b32_e32 v14, v2
	v_mov_b32_e32 v15, v2
	v_mov_b32_e32 v16, v2
	v_mov_b32_e32 v17, v2
	v_mov_b32_e32 v26, v2
	v_mov_b32_e32 v27, v2
	v_mov_b32_e32 v28, v2
	v_mov_b32_e32 v29, v2
	v_mov_b32_e32 v30, v2
	v_mov_b32_e32 v31, v2
	v_mov_b32_e32 v32, v2
	v_mov_b32_e32 v33, v2
	v_mov_b32_e32 v42, v2
	v_mov_b32_e32 v43, v2
	v_mov_b32_e32 v44, v2
	v_mov_b32_e32 v45, v2
	v_mov_b32_e32 v46, v2
	v_mov_b32_e32 v47, v2
	v_mov_b32_e32 v48, v2
	v_mov_b32_e32 v49, v2
	v_mov_b32_e32 v58, v2
	v_mov_b32_e32 v59, v2
	v_mov_b32_e32 v60, v2
	v_mov_b32_e32 v61, v2
	v_mov_b32_e32 v62, v2
	v_mov_b32_e32 v63, v2
	v_mov_b32_e32 v64, v2
	v_mov_b32_e32 v65, v2
	v_mov_b32_e32 v66, v2
	v_mov_b32_e32 v67, v2
	v_mov_b32_e32 v68, v2
	v_mov_b32_e32 v69, v2
	v_mov_b32_e32 v70, v2
	v_mov_b32_e32 v71, v2
	v_mov_b32_e32 v72, v2
	v_mov_b32_e32 v73, v2
	v_mov_b32_e32 v82, v2
	v_mov_b32_e32 v83, v2
	v_mov_b32_e32 v84, v2
	v_mov_b32_e32 v85, v2
	v_mov_b32_e32 v86, v2
	v_mov_b32_e32 v87, v2
	v_mov_b32_e32 v88, v2
	v_mov_b32_e32 v89, v2
	v_mov_b32_e32 v98, v2
	v_mov_b32_e32 v99, v2
	v_mov_b32_e32 v100, v2
	v_mov_b32_e32 v101, v2
	v_mov_b32_e32 v102, v2
	v_mov_b32_e32 v103, v2
	v_mov_b32_e32 v104, v2
	v_mov_b32_e32 v105, v2
	v_mov_b32_e32 v114, v2
	v_mov_b32_e32 v115, v2
	v_mov_b32_e32 v116, v2
	v_mov_b32_e32 v117, v2
	v_mov_b32_e32 v118, v2
	v_mov_b32_e32 v119, v2
	v_mov_b32_e32 v120, v2
	v_mov_b32_e32 v121, v2
	v_mov_b32_e32 v74, v2
	v_mov_b32_e32 v75, v2
	v_mov_b32_e32 v76, v2
	v_mov_b32_e32 v77, v2
	v_mov_b32_e32 v78, v2
	v_mov_b32_e32 v79, v2
	v_mov_b32_e32 v80, v2
	v_mov_b32_e32 v81, v2
	v_mov_b32_e32 v90, v2
	v_mov_b32_e32 v91, v2
	v_mov_b32_e32 v92, v2
	v_mov_b32_e32 v93, v2
	v_mov_b32_e32 v94, v2
	v_mov_b32_e32 v95, v2
	v_mov_b32_e32 v96, v2
	v_mov_b32_e32 v97, v2
	v_mov_b32_e32 v106, v2
	v_mov_b32_e32 v107, v2
	v_mov_b32_e32 v108, v2
	v_mov_b32_e32 v109, v2
	v_mov_b32_e32 v110, v2
	v_mov_b32_e32 v111, v2
	v_mov_b32_e32 v112, v2
	v_mov_b32_e32 v113, v2
	v_mov_b32_e32 v122, v2
	v_mov_b32_e32 v123, v2
	v_mov_b32_e32 v124, v2
	v_mov_b32_e32 v125, v2
	v_mov_b32_e32 v126, v2
	v_mov_b32_e32 v127, v2
	v_mov_b32_e32 v128, v2
	v_mov_b32_e32 v129, v2
	s_nop 0
	s_nop 0
	s_nop 0
	s_nop 0
	s_nop 0
	s_nop 0
	s_nop 0
	s_nop 0
	s_nop 0
	s_nop 0

.LBB0_674:
	s_ashr_i32 s23, s22, 31
	s_lshl_b64 s[0:1], s[22:23], 19
	s_add_u32 s24, s78, s0
	s_addc_u32 s25, s79, s1
	s_and_b64 s[0:1], s[4:5], exec
	s_cselect_b32 s7, s25, s9
	s_cselect_b32 s23, s24, s8
	s_ashr_i32 s21, s20, 31
	s_lshl_b64 s[0:1], s[20:21], 19
	s_add_u32 s26, s19, s0
	s_addc_u32 s27, s33, s1
	s_and_b64 s[0:1], s[4:5], exec
	s_cselect_b32 s21, s27, s3
	s_cselect_b32 s34, s26, s2
	s_add_u32 s8, s8, 0x40080
	s_addc_u32 s9, s9, 0
	s_add_u32 s35, s2, 0x100
	v_mov_b32_e32 v2, 0
	s_addc_u32 s50, s3, 0
	s_mov_b32 s51, -2
	v_mov_b32_e32 v3, v2
	v_mov_b32_e32 v4, v2
	v_mov_b32_e32 v5, v2
	v_mov_b32_e32 v6, v2
	v_mov_b32_e32 v7, v2
	v_mov_b32_e32 v8, v2
	v_mov_b32_e32 v9, v2
	v_mov_b32_e32 v18, v2
	v_mov_b32_e32 v19, v2
	v_mov_b32_e32 v20, v2
	v_mov_b32_e32 v21, v2
	v_mov_b32_e32 v22, v2
	v_mov_b32_e32 v23, v2
	v_mov_b32_e32 v24, v2
	v_mov_b32_e32 v25, v2
	v_mov_b32_e32 v34, v2
	v_mov_b32_e32 v35, v2
	v_mov_b32_e32 v36, v2
	v_mov_b32_e32 v37, v2
	v_mov_b32_e32 v38, v2
	v_mov_b32_e32 v39, v2
	v_mov_b32_e32 v40, v2
	v_mov_b32_e32 v41, v2
	v_mov_b32_e32 v50, v2
	v_mov_b32_e32 v51, v2
	v_mov_b32_e32 v52, v2
	v_mov_b32_e32 v53, v2
	v_mov_b32_e32 v54, v2
	v_mov_b32_e32 v55, v2
	v_mov_b32_e32 v56, v2
	v_mov_b32_e32 v57, v2
	v_mov_b32_e32 v10, v2
	v_mov_b32_e32 v11, v2
	v_mov_b32_e32 v12, v2
	v_mov_b32_e32 v13, v2
	v_mov_b32_e32 v14, v2
	v_mov_b32_e32 v15, v2
	v_mov_b32_e32 v16, v2
	v_mov_b32_e32 v17, v2
	v_mov_b32_e32 v26, v2
	v_mov_b32_e32 v27, v2
	v_mov_b32_e32 v28, v2
	v_mov_b32_e32 v29, v2
	v_mov_b32_e32 v30, v2
	v_mov_b32_e32 v31, v2
	v_mov_b32_e32 v32, v2
	v_mov_b32_e32 v33, v2
	v_mov_b32_e32 v42, v2
	v_mov_b32_e32 v43, v2
	v_mov_b32_e32 v44, v2
	v_mov_b32_e32 v45, v2
	v_mov_b32_e32 v46, v2
	v_mov_b32_e32 v47, v2
	v_mov_b32_e32 v48, v2
	v_mov_b32_e32 v49, v2
	v_mov_b32_e32 v58, v2
	v_mov_b32_e32 v59, v2
	v_mov_b32_e32 v60, v2
	v_mov_b32_e32 v61, v2
	v_mov_b32_e32 v62, v2
	v_mov_b32_e32 v63, v2
	v_mov_b32_e32 v64, v2
	v_mov_b32_e32 v65, v2
	v_mov_b32_e32 v66, v2
	v_mov_b32_e32 v67, v2
	v_mov_b32_e32 v68, v2
	v_mov_b32_e32 v69, v2
	v_mov_b32_e32 v70, v2
	v_mov_b32_e32 v71, v2
	v_mov_b32_e32 v72, v2
	v_mov_b32_e32 v73, v2
	v_mov_b32_e32 v90, v2
	v_mov_b32_e32 v91, v2
	v_mov_b32_e32 v92, v2
	v_mov_b32_e32 v93, v2
	v_mov_b32_e32 v98, v2
	v_mov_b32_e32 v99, v2
	v_mov_b32_e32 v100, v2
	v_mov_b32_e32 v101, v2
	v_mov_b32_e32 v122, v2
	v_mov_b32_e32 v123, v2
	v_mov_b32_e32 v124, v2
	v_mov_b32_e32 v125, v2
	v_mov_b32_e32 v126, v2
	v_mov_b32_e32 v127, v2
	v_mov_b32_e32 v128, v2
	v_mov_b32_e32 v129, v2
	v_mov_b32_e32 v142, v2
	v_mov_b32_e32 v143, v2
	v_mov_b32_e32 v144, v2
	v_mov_b32_e32 v145, v2
	v_mov_b32_e32 v146, v2
	v_mov_b32_e32 v147, v2
	v_mov_b32_e32 v148, v2
	v_mov_b32_e32 v149, v2
	v_mov_b32_e32 v74, v2
	v_mov_b32_e32 v75, v2
	v_mov_b32_e32 v76, v2
	v_mov_b32_e32 v77, v2
	v_mov_b32_e32 v78, v2
	v_mov_b32_e32 v79, v2
	v_mov_b32_e32 v80, v2
	v_mov_b32_e32 v81, v2
	v_mov_b32_e32 v106, v2
	v_mov_b32_e32 v107, v2
	v_mov_b32_e32 v108, v2
	v_mov_b32_e32 v109, v2
	v_mov_b32_e32 v114, v2
	v_mov_b32_e32 v115, v2
	v_mov_b32_e32 v116, v2
	v_mov_b32_e32 v117, v2
	v_mov_b32_e32 v130, v2
	v_mov_b32_e32 v131, v2
	v_mov_b32_e32 v132, v2
	v_mov_b32_e32 v133, v2
	v_mov_b32_e32 v134, v2
	v_mov_b32_e32 v135, v2
	v_mov_b32_e32 v136, v2
	v_mov_b32_e32 v137, v2
	v_mov_b32_e32 v150, v2
	v_mov_b32_e32 v151, v2
	v_mov_b32_e32 v152, v2
	v_mov_b32_e32 v153, v2
	v_mov_b32_e32 v154, v2
	v_mov_b32_e32 v155, v2
	v_mov_b32_e32 v156, v2
	v_mov_b32_e32 v157, v2
	s_nop 0
	s_nop 0
	s_nop 0
	s_nop 0
	s_nop 0
	s_nop 0
	s_nop 0
	s_nop 0
	s_nop 0
	s_nop 0
	s_nop 0
	s_nop 0
	s_nop 0

.LBB0_1213:
	s_and_b32 s99, s56, 1
	s_lshl_b32 s99, s99, 12
	v_readfirstlane_b32 s100, v0
	s_and_b32 s100, s100, 0xc0
	s_lshl_b32 s100, s100, 4
	s_add_i32 s99, s99, s100
	s_add_i32 m0, s99, 0x21000
	s_lshl_b32 s99, s8, 12
	s_add_u32 s100, s76, s99
	s_addc_u32 s101, s77, 0
	v_and_b32_e32 v149, 0xff, v0
	v_lshlrev_b32_e32 v149, 4, v149
	global_load_lds_dwordx4 v149, s[100:101]
	s_ashr_i32 s31, s30, 31
	s_lshl_b64 s[0:1], s[30:31], 19
	s_add_u32 s34, s78, s0
	s_addc_u32 s35, s79, s1
	s_and_b64 s[0:1], s[4:5], exec
	s_cselect_b32 s7, s35, s39
	s_cselect_b32 s9, s34, s38
	s_ashr_i32 s29, s28, 31
	s_lshl_b64 s[0:1], s[28:29], 19
	s_add_u32 s36, s27, s0
	s_addc_u32 s37, s33, s1
	s_and_b64 s[0:1], s[4:5], exec
	s_cselect_b32 s10, s37, s3
	s_cselect_b32 s29, s36, s2
	s_add_u32 s38, s38, 0x40080
	s_addc_u32 s39, s39, 0
	s_add_u32 s31, s2, 0x100
	v_mov_b32_e32 v2, 0
	s_addc_u32 s57, s3, 0
	s_mov_b32 s58, -2
	v_mov_b32_e32 v3, v2
	v_mov_b32_e32 v4, v2
	v_mov_b32_e32 v5, v2
	v_mov_b32_e32 v6, v2
	v_mov_b32_e32 v7, v2
	v_mov_b32_e32 v8, v2
	v_mov_b32_e32 v9, v2
	v_mov_b32_e32 v18, v2
	v_mov_b32_e32 v19, v2
	v_mov_b32_e32 v20, v2
	v_mov_b32_e32 v21, v2
	v_mov_b32_e32 v22, v2
	v_mov_b32_e32 v23, v2
	v_mov_b32_e32 v24, v2
	v_mov_b32_e32 v25, v2
	v_mov_b32_e32 v34, v2
	v_mov_b32_e32 v35, v2
	v_mov_b32_e32 v36, v2
	v_mov_b32_e32 v37, v2
	v_mov_b32_e32 v38, v2
	v_mov_b32_e32 v39, v2
	v_mov_b32_e32 v40, v2
	v_mov_b32_e32 v41, v2
	v_mov_b32_e32 v50, v2
	v_mov_b32_e32 v51, v2
	v_mov_b32_e32 v52, v2
	v_mov_b32_e32 v53, v2
	v_mov_b32_e32 v54, v2
	v_mov_b32_e32 v55, v2
	v_mov_b32_e32 v56, v2
	v_mov_b32_e32 v57, v2
	v_mov_b32_e32 v10, v2
	v_mov_b32_e32 v11, v2
	v_mov_b32_e32 v12, v2
	v_mov_b32_e32 v13, v2
	v_mov_b32_e32 v14, v2
	v_mov_b32_e32 v15, v2
	v_mov_b32_e32 v16, v2
	v_mov_b32_e32 v17, v2
	v_mov_b32_e32 v26, v2
	v_mov_b32_e32 v27, v2
	v_mov_b32_e32 v28, v2
	v_mov_b32_e32 v29, v2
	v_mov_b32_e32 v30, v2
	v_mov_b32_e32 v31, v2
	v_mov_b32_e32 v32, v2
	v_mov_b32_e32 v33, v2
	v_mov_b32_e32 v42, v2
	v_mov_b32_e32 v43, v2
	v_mov_b32_e32 v44, v2
	v_mov_b32_e32 v45, v2
	v_mov_b32_e32 v46, v2
	v_mov_b32_e32 v47, v2
	v_mov_b32_e32 v48, v2
	v_mov_b32_e32 v49, v2
	v_mov_b32_e32 v58, v2
	v_mov_b32_e32 v59, v2
	v_mov_b32_e32 v60, v2
	v_mov_b32_e32 v61, v2
	v_mov_b32_e32 v66, v2
	v_mov_b32_e32 v67, v2
	v_mov_b32_e32 v68, v2
	v_mov_b32_e32 v69, v2
	v_mov_b32_e32 v70, v2
	v_mov_b32_e32 v71, v2
	v_mov_b32_e32 v72, v2
	v_mov_b32_e32 v73, v2
	v_mov_b32_e32 v74, v2
	v_mov_b32_e32 v75, v2
	v_mov_b32_e32 v76, v2
	v_mov_b32_e32 v77, v2
	v_mov_b32_e32 v90, v2
	v_mov_b32_e32 v91, v2
	v_mov_b32_e32 v92, v2
	v_mov_b32_e32 v93, v2
	v_mov_b32_e32 v94, v2
	v_mov_b32_e32 v95, v2
	v_mov_b32_e32 v96, v2
	v_mov_b32_e32 v97, v2
	v_mov_b32_e32 v110, v2
	v_mov_b32_e32 v111, v2
	v_mov_b32_e32 v112, v2
	v_mov_b32_e32 v113, v2
	v_mov_b32_e32 v114, v2
	v_mov_b32_e32 v115, v2
	v_mov_b32_e32 v116, v2
	v_mov_b32_e32 v117, v2
	v_mov_b32_e32 v130, v2
	v_mov_b32_e32 v131, v2
	v_mov_b32_e32 v132, v2
	v_mov_b32_e32 v133, v2
	v_mov_b32_e32 v134, v2
	v_mov_b32_e32 v135, v2
	v_mov_b32_e32 v136, v2
	v_mov_b32_e32 v137, v2
	v_mov_b32_e32 v82, v2
	v_mov_b32_e32 v83, v2
	v_mov_b32_e32 v84, v2
	v_mov_b32_e32 v85, v2
	v_mov_b32_e32 v86, v2
	v_mov_b32_e32 v87, v2
	v_mov_b32_e32 v88, v2
	v_mov_b32_e32 v89, v2
	v_mov_b32_e32 v102, v2
	v_mov_b32_e32 v103, v2
	v_mov_b32_e32 v104, v2
	v_mov_b32_e32 v105, v2
	v_mov_b32_e32 v106, v2
	v_mov_b32_e32 v107, v2
	v_mov_b32_e32 v108, v2
	v_mov_b32_e32 v109, v2
	v_mov_b32_e32 v122, v2
	v_mov_b32_e32 v123, v2
	v_mov_b32_e32 v124, v2
	v_mov_b32_e32 v125, v2
	v_mov_b32_e32 v126, v2
	v_mov_b32_e32 v127, v2
	v_mov_b32_e32 v128, v2
	v_mov_b32_e32 v129, v2
	v_mov_b32_e32 v142, v2
	v_mov_b32_e32 v143, v2
	v_mov_b32_e32 v144, v2
	v_mov_b32_e32 v145, v2
	v_mov_b32_e32 v146, v2
	v_mov_b32_e32 v147, v2
	v_mov_b32_e32 v148, v2
	v_mov_b32_e32 v149, v2
	s_nop 0
	s_nop 0
	s_nop 0
	s_nop 0
	s_nop 0
	s_nop 0

.LBB0_1625:
	s_ashr_i32 s29, s28, 31
	s_lshl_b64 s[0:1], s[28:29], 20
	s_add_u32 s30, s33, s0
	s_addc_u32 s31, s42, s1
	s_and_b64 s[0:1], s[6:7], exec
	s_cselect_b32 s11, s31, s39
	s_cselect_b32 s29, s30, s38
	s_ashr_i32 s27, s26, 31
	s_lshl_b64 s[0:1], s[26:27], 20
	s_add_u32 s34, s43, s0
	s_addc_u32 s35, s44, s1
	s_and_b64 s[0:1], s[6:7], exec
	s_cselect_b32 s27, s35, s3
	s_cselect_b32 s56, s34, s2
	s_add_u32 s38, s38, 0x80080
	s_addc_u32 s39, s39, 0
	s_add_u32 s57, s2, 0x100
	v_mov_b32_e32 v2, 0
	s_addc_u32 s58, s3, 0
	s_mov_b32 s59, -2
	s_waitcnt lgkmcnt(0)
	v_mov_b32_e32 v3, v2
	v_mov_b32_e32 v4, v2
	v_mov_b32_e32 v5, v2
	v_mov_b32_e32 v6, v2
	v_mov_b32_e32 v7, v2
	v_mov_b32_e32 v8, v2
	v_mov_b32_e32 v9, v2
	v_mov_b32_e32 v18, v2
	v_mov_b32_e32 v19, v2
	v_mov_b32_e32 v20, v2
	v_mov_b32_e32 v21, v2
	v_mov_b32_e32 v22, v2
	v_mov_b32_e32 v23, v2
	v_mov_b32_e32 v24, v2
	v_mov_b32_e32 v25, v2
	v_mov_b32_e32 v34, v2
	v_mov_b32_e32 v35, v2
	v_mov_b32_e32 v36, v2
	v_mov_b32_e32 v37, v2
	v_mov_b32_e32 v38, v2
	v_mov_b32_e32 v39, v2
	v_mov_b32_e32 v40, v2
	v_mov_b32_e32 v41, v2
	v_mov_b32_e32 v50, v2
	v_mov_b32_e32 v51, v2
	v_mov_b32_e32 v52, v2
	v_mov_b32_e32 v53, v2
	v_mov_b32_e32 v54, v2
	v_mov_b32_e32 v55, v2
	v_mov_b32_e32 v56, v2
	v_mov_b32_e32 v57, v2
	v_mov_b32_e32 v10, v2
	v_mov_b32_e32 v11, v2
	v_mov_b32_e32 v12, v2
	v_mov_b32_e32 v13, v2
	v_mov_b32_e32 v14, v2
	v_mov_b32_e32 v15, v2
	v_mov_b32_e32 v16, v2
	v_mov_b32_e32 v17, v2
	v_mov_b32_e32 v26, v2
	v_mov_b32_e32 v27, v2
	v_mov_b32_e32 v28, v2
	v_mov_b32_e32 v29, v2
	v_mov_b32_e32 v30, v2
	v_mov_b32_e32 v31, v2
	v_mov_b32_e32 v32, v2
	v_mov_b32_e32 v33, v2
	v_mov_b32_e32 v42, v2
	v_mov_b32_e32 v43, v2
	v_mov_b32_e32 v44, v2
	v_mov_b32_e32 v45, v2
	v_mov_b32_e32 v46, v2
	v_mov_b32_e32 v47, v2
	v_mov_b32_e32 v48, v2
	v_mov_b32_e32 v49, v2
	v_mov_b32_e32 v58, v2
	v_mov_b32_e32 v59, v2
	v_mov_b32_e32 v60, v2
	v_mov_b32_e32 v61, v2
	v_mov_b32_e32 v62, v2
	v_mov_b32_e32 v63, v2
	v_mov_b32_e32 v64, v2
	v_mov_b32_e32 v65, v2
	v_mov_b32_e32 v66, v2
	v_mov_b32_e32 v67, v2
	v_mov_b32_e32 v68, v2
	v_mov_b32_e32 v69, v2
	v_mov_b32_e32 v70, v2
	v_mov_b32_e32 v71, v2
	v_mov_b32_e32 v72, v2
	v_mov_b32_e32 v73, v2
	v_mov_b32_e32 v82, v2
	v_mov_b32_e32 v83, v2
	v_mov_b32_e32 v84, v2
	v_mov_b32_e32 v85, v2
	v_mov_b32_e32 v86, v2
	v_mov_b32_e32 v87, v2
	v_mov_b32_e32 v88, v2
	v_mov_b32_e32 v89, v2
	v_mov_b32_e32 v98, v2
	v_mov_b32_e32 v99, v2
	v_mov_b32_e32 v100, v2
	v_mov_b32_e32 v101, v2
	v_mov_b32_e32 v102, v2
	v_mov_b32_e32 v103, v2
	v_mov_b32_e32 v104, v2
	v_mov_b32_e32 v105, v2
	v_mov_b32_e32 v114, v2
	v_mov_b32_e32 v115, v2
	v_mov_b32_e32 v116, v2
	v_mov_b32_e32 v117, v2
	v_mov_b32_e32 v118, v2
	v_mov_b32_e32 v119, v2
	v_mov_b32_e32 v120, v2
	v_mov_b32_e32 v121, v2
	v_mov_b32_e32 v74, v2
	v_mov_b32_e32 v75, v2
	v_mov_b32_e32 v76, v2
	v_mov_b32_e32 v77, v2
	v_mov_b32_e32 v78, v2
	v_mov_b32_e32 v79, v2
	v_mov_b32_e32 v80, v2
	v_mov_b32_e32 v81, v2
	v_mov_b32_e32 v90, v2
	v_mov_b32_e32 v91, v2
	v_mov_b32_e32 v92, v2
	v_mov_b32_e32 v93, v2
	v_mov_b32_e32 v94, v2
	v_mov_b32_e32 v95, v2
	v_mov_b32_e32 v96, v2
	v_mov_b32_e32 v97, v2
	v_mov_b32_e32 v106, v2
	v_mov_b32_e32 v107, v2
	v_mov_b32_e32 v108, v2
	v_mov_b32_e32 v109, v2
	v_mov_b32_e32 v110, v2
	v_mov_b32_e32 v111, v2
	v_mov_b32_e32 v112, v2
	v_mov_b32_e32 v113, v2
	v_mov_b32_e32 v122, v2
	v_mov_b32_e32 v123, v2
	v_mov_b32_e32 v124, v2
	v_mov_b32_e32 v125, v2
	v_mov_b32_e32 v126, v2
	v_mov_b32_e32 v127, v2
	v_mov_b32_e32 v128, v2
	v_mov_b32_e32 v129, v2
	s_nop 0
	s_nop 0
	s_nop 0
	s_nop 0

.LBB0_1714:
	s_and_b32 s99, s47, 1
	s_lshl_b32 s99, s99, 12
	v_readfirstlane_b32 s100, v0
	s_and_b32 s100, s100, 0xc0
	s_lshl_b32 s100, s100, 4
	s_add_i32 s99, s99, s100
	s_add_i32 m0, s99, 0x21000
	s_lshl_b32 s99, s26, 12
	s_add_u32 s100, s76, s99
	s_addc_u32 s101, s77, 0
	v_and_b32_e32 v129, 0xff, v0
	v_lshlrev_b32_e32 v129, 4, v129
	global_load_lds_dwordx4 v129, s[100:101]
	s_ashr_i32 s21, s20, 31
	s_lshl_b64 s[0:1], s[20:21], 19
	s_add_u32 s22, s78, s0
	s_addc_u32 s23, s79, s1
	s_and_b64 s[0:1], s[4:5], exec
	s_cselect_b32 s21, s23, s29
	s_cselect_b32 s49, s22, s28
	s_ashr_i32 s19, s18, 31
	s_lshl_b64 s[0:1], s[18:19], 19
	s_add_u32 s24, s33, s0
	s_addc_u32 s25, s34, s1
	s_and_b64 s[0:1], s[4:5], exec
	s_cselect_b32 s19, s25, s3
	s_cselect_b32 s50, s24, s2
	s_add_u32 s28, s28, 0x40080
	s_addc_u32 s29, s29, 0
	s_add_u32 s51, s2, 0x100
	v_mov_b32_e32 v2, 0
	s_addc_u32 s52, s3, 0
	s_mov_b32 s53, -2
	v_mov_b32_e32 v3, v2
	v_mov_b32_e32 v4, v2
	v_mov_b32_e32 v5, v2
	v_mov_b32_e32 v10, v2
	v_mov_b32_e32 v11, v2
	v_mov_b32_e32 v12, v2
	v_mov_b32_e32 v13, v2
	v_mov_b32_e32 v18, v2
	v_mov_b32_e32 v19, v2
	v_mov_b32_e32 v20, v2
	v_mov_b32_e32 v21, v2
	v_mov_b32_e32 v26, v2
	v_mov_b32_e32 v27, v2
	v_mov_b32_e32 v28, v2
	v_mov_b32_e32 v29, v2
	v_mov_b32_e32 v34, v2
	v_mov_b32_e32 v35, v2
	v_mov_b32_e32 v36, v2
	v_mov_b32_e32 v37, v2
	v_mov_b32_e32 v42, v2
	v_mov_b32_e32 v43, v2
	v_mov_b32_e32 v44, v2
	v_mov_b32_e32 v45, v2
	v_mov_b32_e32 v50, v2
	v_mov_b32_e32 v51, v2
	v_mov_b32_e32 v52, v2
	v_mov_b32_e32 v53, v2
	v_mov_b32_e32 v58, v2
	v_mov_b32_e32 v59, v2
	v_mov_b32_e32 v60, v2
	v_mov_b32_e32 v61, v2
	v_mov_b32_e32 v6, v2
	v_mov_b32_e32 v7, v2
	v_mov_b32_e32 v8, v2
	v_mov_b32_e32 v9, v2
	v_mov_b32_e32 v14, v2
	v_mov_b32_e32 v15, v2
	v_mov_b32_e32 v16, v2
	v_mov_b32_e32 v17, v2
	v_mov_b32_e32 v22, v2
	v_mov_b32_e32 v23, v2
	v_mov_b32_e32 v24, v2
	v_mov_b32_e32 v25, v2
	v_mov_b32_e32 v30, v2
	v_mov_b32_e32 v31, v2
	v_mov_b32_e32 v32, v2
	v_mov_b32_e32 v33, v2
	v_mov_b32_e32 v38, v2
	v_mov_b32_e32 v39, v2
	v_mov_b32_e32 v40, v2
	v_mov_b32_e32 v41, v2
	v_mov_b32_e32 v46, v2
	v_mov_b32_e32 v47, v2
	v_mov_b32_e32 v48, v2
	v_mov_b32_e32 v49, v2
	v_mov_b32_e32 v54, v2
	v_mov_b32_e32 v55, v2
	v_mov_b32_e32 v56, v2
	v_mov_b32_e32 v57, v2
	v_mov_b32_e32 v62, v2
	v_mov_b32_e32 v63, v2
	v_mov_b32_e32 v64, v2
	v_mov_b32_e32 v65, v2
	v_mov_b32_e32 v66, v2
	v_mov_b32_e32 v67, v2
	v_mov_b32_e32 v68, v2
	v_mov_b32_e32 v69, v2
	v_mov_b32_e32 v74, v2
	v_mov_b32_e32 v75, v2
	v_mov_b32_e32 v76, v2
	v_mov_b32_e32 v77, v2
	v_mov_b32_e32 v82, v2
	v_mov_b32_e32 v83, v2
	v_mov_b32_e32 v84, v2
	v_mov_b32_e32 v85, v2
	v_mov_b32_e32 v90, v2
	v_mov_b32_e32 v91, v2
	v_mov_b32_e32 v92, v2
	v_mov_b32_e32 v93, v2
	v_mov_b32_e32 v98, v2
	v_mov_b32_e32 v99, v2
	v_mov_b32_e32 v100, v2
	v_mov_b32_e32 v101, v2
	v_mov_b32_e32 v106, v2
	v_mov_b32_e32 v107, v2
	v_mov_b32_e32 v108, v2
	v_mov_b32_e32 v109, v2
	v_mov_b32_e32 v114, v2
	v_mov_b32_e32 v115, v2
	v_mov_b32_e32 v116, v2
	v_mov_b32_e32 v117, v2
	v_mov_b32_e32 v122, v2
	v_mov_b32_e32 v123, v2
	v_mov_b32_e32 v124, v2
	v_mov_b32_e32 v125, v2
	v_mov_b32_e32 v70, v2
	v_mov_b32_e32 v71, v2
	v_mov_b32_e32 v72, v2
	v_mov_b32_e32 v73, v2
	v_mov_b32_e32 v78, v2
	v_mov_b32_e32 v79, v2
	v_mov_b32_e32 v80, v2
	v_mov_b32_e32 v81, v2
	v_mov_b32_e32 v86, v2
	v_mov_b32_e32 v87, v2
	v_mov_b32_e32 v88, v2
	v_mov_b32_e32 v89, v2
	v_mov_b32_e32 v94, v2
	v_mov_b32_e32 v95, v2
	v_mov_b32_e32 v96, v2
	v_mov_b32_e32 v97, v2
	v_mov_b32_e32 v102, v2
	v_mov_b32_e32 v103, v2
	v_mov_b32_e32 v104, v2
	v_mov_b32_e32 v105, v2
	v_mov_b32_e32 v110, v2
	v_mov_b32_e32 v111, v2
	v_mov_b32_e32 v112, v2
	v_mov_b32_e32 v113, v2
	v_mov_b32_e32 v118, v2
	v_mov_b32_e32 v119, v2
	v_mov_b32_e32 v120, v2
	v_mov_b32_e32 v121, v2
	v_mov_b32_e32 v126, v2
	v_mov_b32_e32 v127, v2
	v_mov_b32_e32 v128, v2
	v_mov_b32_e32 v129, v2
	s_nop 0
	s_nop 0
	s_nop 0
	s_nop 0
	s_nop 0
	s_nop 0
	s_nop 0
	s_nop 0
	s_nop 0
	s_nop 0

.LBB0_1840:
	s_add_u32 s30, s30, 0xb0080
	s_addc_u32 s31, s31, 0
	s_add_u32 s53, s2, 0x100
	v_mov_b32_e32 v2, 0
	s_addc_u32 s54, s3, 0
	s_mov_b32 s55, -2
	s_waitcnt lgkmcnt(0)
	v_mov_b32_e32 v3, v2
	v_mov_b32_e32 v4, v2
	v_mov_b32_e32 v5, v2
	v_mov_b32_e32 v6, v2
	v_mov_b32_e32 v7, v2
	v_mov_b32_e32 v8, v2
	v_mov_b32_e32 v9, v2
	v_mov_b32_e32 v18, v2
	v_mov_b32_e32 v19, v2
	v_mov_b32_e32 v20, v2
	v_mov_b32_e32 v21, v2
	v_mov_b32_e32 v22, v2
	v_mov_b32_e32 v23, v2
	v_mov_b32_e32 v24, v2
	v_mov_b32_e32 v25, v2
	v_mov_b32_e32 v34, v2
	v_mov_b32_e32 v35, v2
	v_mov_b32_e32 v36, v2
	v_mov_b32_e32 v37, v2
	v_mov_b32_e32 v38, v2
	v_mov_b32_e32 v39, v2
	v_mov_b32_e32 v40, v2
	v_mov_b32_e32 v41, v2
	v_mov_b32_e32 v50, v2
	v_mov_b32_e32 v51, v2
	v_mov_b32_e32 v52, v2
	v_mov_b32_e32 v53, v2
	v_mov_b32_e32 v54, v2
	v_mov_b32_e32 v55, v2
	v_mov_b32_e32 v56, v2
	v_mov_b32_e32 v57, v2
	v_mov_b32_e32 v10, v2
	v_mov_b32_e32 v11, v2
	v_mov_b32_e32 v12, v2
	v_mov_b32_e32 v13, v2
	v_mov_b32_e32 v14, v2
	v_mov_b32_e32 v15, v2
	v_mov_b32_e32 v16, v2
	v_mov_b32_e32 v17, v2
	v_mov_b32_e32 v26, v2
	v_mov_b32_e32 v27, v2
	v_mov_b32_e32 v28, v2
	v_mov_b32_e32 v29, v2
	v_mov_b32_e32 v30, v2
	v_mov_b32_e32 v31, v2
	v_mov_b32_e32 v32, v2
	v_mov_b32_e32 v33, v2
	v_mov_b32_e32 v42, v2
	v_mov_b32_e32 v43, v2
	v_mov_b32_e32 v44, v2
	v_mov_b32_e32 v45, v2
	v_mov_b32_e32 v46, v2
	v_mov_b32_e32 v47, v2
	v_mov_b32_e32 v48, v2
	v_mov_b32_e32 v49, v2
	v_mov_b32_e32 v58, v2
	v_mov_b32_e32 v59, v2
	v_mov_b32_e32 v60, v2
	v_mov_b32_e32 v61, v2
	v_mov_b32_e32 v62, v2
	v_mov_b32_e32 v63, v2
	v_mov_b32_e32 v64, v2
	v_mov_b32_e32 v65, v2
	v_mov_b32_e32 v66, v2
	v_mov_b32_e32 v67, v2
	v_mov_b32_e32 v68, v2
	v_mov_b32_e32 v69, v2
	v_mov_b32_e32 v70, v2
	v_mov_b32_e32 v71, v2
	v_mov_b32_e32 v72, v2
	v_mov_b32_e32 v73, v2
	v_mov_b32_e32 v82, v2
	v_mov_b32_e32 v83, v2
	v_mov_b32_e32 v84, v2
	v_mov_b32_e32 v85, v2
	v_mov_b32_e32 v86, v2
	v_mov_b32_e32 v87, v2
	v_mov_b32_e32 v88, v2
	v_mov_b32_e32 v89, v2
	v_mov_b32_e32 v98, v2
	v_mov_b32_e32 v99, v2
	v_mov_b32_e32 v100, v2
	v_mov_b32_e32 v101, v2
	v_mov_b32_e32 v102, v2
	v_mov_b32_e32 v103, v2
	v_mov_b32_e32 v104, v2
	v_mov_b32_e32 v105, v2
	v_mov_b32_e32 v114, v2
	v_mov_b32_e32 v115, v2
	v_mov_b32_e32 v116, v2
	v_mov_b32_e32 v117, v2
	v_mov_b32_e32 v118, v2
	v_mov_b32_e32 v119, v2
	v_mov_b32_e32 v120, v2
	v_mov_b32_e32 v121, v2
	v_mov_b32_e32 v74, v2
	v_mov_b32_e32 v75, v2
	v_mov_b32_e32 v76, v2
	v_mov_b32_e32 v77, v2
	v_mov_b32_e32 v78, v2
	v_mov_b32_e32 v79, v2
	v_mov_b32_e32 v80, v2
	v_mov_b32_e32 v81, v2
	v_mov_b32_e32 v90, v2
	v_mov_b32_e32 v91, v2
	v_mov_b32_e32 v92, v2
	v_mov_b32_e32 v93, v2
	v_mov_b32_e32 v94, v2
	v_mov_b32_e32 v95, v2
	v_mov_b32_e32 v96, v2
	v_mov_b32_e32 v97, v2
	v_mov_b32_e32 v106, v2
	v_mov_b32_e32 v107, v2
	v_mov_b32_e32 v108, v2
	v_mov_b32_e32 v109, v2
	v_mov_b32_e32 v110, v2
	v_mov_b32_e32 v111, v2
	v_mov_b32_e32 v112, v2
	v_mov_b32_e32 v113, v2
	v_mov_b32_e32 v122, v2
	v_mov_b32_e32 v123, v2
	v_mov_b32_e32 v124, v2
	v_mov_b32_e32 v125, v2
	v_mov_b32_e32 v126, v2
	v_mov_b32_e32 v127, v2
	v_mov_b32_e32 v128, v2
	v_mov_b32_e32 v129, v2
	s_nop 0

.LBB0_1937:
	s_and_b32 s99, s45, 1
	s_lshl_b32 s99, s99, 12
	v_readfirstlane_b32 s100, v0
	s_and_b32 s100, s100, 0xc0
	s_lshl_b32 s100, s100, 4
	s_add_i32 s99, s99, s100
	s_add_i32 m0, s99, 0x21000
	s_lshl_b32 s99, s26, 12
	s_add_u32 s100, s76, s99
	s_addc_u32 s101, s77, 0
	v_and_b32_e32 v129, 0xff, v0
	v_lshlrev_b32_e32 v129, 4, v129
	global_load_lds_dwordx4 v129, s[100:101]
	s_ashr_i32 s21, s20, 31
	s_lshl_b64 s[0:1], s[20:21], 19
	s_add_u32 s22, s78, s0
	s_addc_u32 s23, s79, s1
	s_and_b64 s[0:1], s[4:5], exec
	s_cselect_b32 s21, s23, s29
	s_cselect_b32 s47, s22, s28
	s_ashr_i32 s19, s18, 31
	s_lshl_b64 s[0:1], s[18:19], 19
	s_add_u32 s24, s34, s0
	s_addc_u32 s25, s35, s1
	s_and_b64 s[0:1], s[4:5], exec
	s_cselect_b32 s19, s25, s3
	s_cselect_b32 s48, s24, s2
	s_add_u32 s28, s28, 0x40080
	s_addc_u32 s29, s29, 0
	s_add_u32 s49, s2, 0x100
	v_mov_b32_e32 v2, 0
	s_addc_u32 s50, s3, 0
	s_mov_b32 s51, -2
	v_mov_b32_e32 v3, v2
	v_mov_b32_e32 v4, v2
	v_mov_b32_e32 v5, v2
	v_mov_b32_e32 v6, v2
	v_mov_b32_e32 v7, v2
	v_mov_b32_e32 v8, v2
	v_mov_b32_e32 v9, v2
	v_mov_b32_e32 v18, v2
	v_mov_b32_e32 v19, v2
	v_mov_b32_e32 v20, v2
	v_mov_b32_e32 v21, v2
	v_mov_b32_e32 v22, v2
	v_mov_b32_e32 v23, v2
	v_mov_b32_e32 v24, v2
	v_mov_b32_e32 v25, v2
	v_mov_b32_e32 v34, v2
	v_mov_b32_e32 v35, v2
	v_mov_b32_e32 v36, v2
	v_mov_b32_e32 v37, v2
	v_mov_b32_e32 v38, v2
	v_mov_b32_e32 v39, v2
	v_mov_b32_e32 v40, v2
	v_mov_b32_e32 v41, v2
	v_mov_b32_e32 v50, v2
	v_mov_b32_e32 v51, v2
	v_mov_b32_e32 v52, v2
	v_mov_b32_e32 v53, v2
	v_mov_b32_e32 v54, v2
	v_mov_b32_e32 v55, v2
	v_mov_b32_e32 v56, v2
	v_mov_b32_e32 v57, v2
	v_mov_b32_e32 v10, v2
	v_mov_b32_e32 v11, v2
	v_mov_b32_e32 v12, v2
	v_mov_b32_e32 v13, v2
	v_mov_b32_e32 v14, v2
	v_mov_b32_e32 v15, v2
	v_mov_b32_e32 v16, v2
	v_mov_b32_e32 v17, v2
	v_mov_b32_e32 v26, v2
	v_mov_b32_e32 v27, v2
	v_mov_b32_e32 v28, v2
	v_mov_b32_e32 v29, v2
	v_mov_b32_e32 v30, v2
	v_mov_b32_e32 v31, v2
	v_mov_b32_e32 v32, v2
	v_mov_b32_e32 v33, v2
	v_mov_b32_e32 v42, v2
	v_mov_b32_e32 v43, v2
	v_mov_b32_e32 v44, v2
	v_mov_b32_e32 v45, v2
	v_mov_b32_e32 v46, v2
	v_mov_b32_e32 v47, v2
	v_mov_b32_e32 v48, v2
	v_mov_b32_e32 v49, v2
	v_mov_b32_e32 v58, v2
	v_mov_b32_e32 v59, v2
	v_mov_b32_e32 v60, v2
	v_mov_b32_e32 v61, v2
	v_mov_b32_e32 v62, v2
	v_mov_b32_e32 v63, v2
	v_mov_b32_e32 v64, v2
	v_mov_b32_e32 v65, v2
	v_mov_b32_e32 v66, v2
	v_mov_b32_e32 v67, v2
	v_mov_b32_e32 v68, v2
	v_mov_b32_e32 v69, v2
	v_mov_b32_e32 v70, v2
	v_mov_b32_e32 v71, v2
	v_mov_b32_e32 v72, v2
	v_mov_b32_e32 v73, v2
	v_mov_b32_e32 v82, v2
	v_mov_b32_e32 v83, v2
	v_mov_b32_e32 v84, v2
	v_mov_b32_e32 v85, v2
	v_mov_b32_e32 v86, v2
	v_mov_b32_e32 v87, v2
	v_mov_b32_e32 v88, v2
	v_mov_b32_e32 v89, v2
	v_mov_b32_e32 v98, v2
	v_mov_b32_e32 v99, v2
	v_mov_b32_e32 v100, v2
	v_mov_b32_e32 v101, v2
	v_mov_b32_e32 v102, v2
	v_mov_b32_e32 v103, v2
	v_mov_b32_e32 v104, v2
	v_mov_b32_e32 v105, v2
	v_mov_b32_e32 v114, v2
	v_mov_b32_e32 v115, v2
	v_mov_b32_e32 v116, v2
	v_mov_b32_e32 v117, v2
	v_mov_b32_e32 v122, v2
	v_mov_b32_e32 v123, v2
	v_mov_b32_e32 v124, v2
	v_mov_b32_e32 v125, v2
	v_mov_b32_e32 v74, v2
	v_mov_b32_e32 v75, v2
	v_mov_b32_e32 v76, v2
	v_mov_b32_e32 v77, v2
	v_mov_b32_e32 v78, v2
	v_mov_b32_e32 v79, v2
	v_mov_b32_e32 v80, v2
	v_mov_b32_e32 v81, v2
	v_mov_b32_e32 v90, v2
	v_mov_b32_e32 v91, v2
	v_mov_b32_e32 v92, v2
	v_mov_b32_e32 v93, v2
	v_mov_b32_e32 v94, v2
	v_mov_b32_e32 v95, v2
	v_mov_b32_e32 v96, v2
	v_mov_b32_e32 v97, v2
	v_mov_b32_e32 v106, v2
	v_mov_b32_e32 v107, v2
	v_mov_b32_e32 v108, v2
	v_mov_b32_e32 v109, v2
	v_mov_b32_e32 v110, v2
	v_mov_b32_e32 v111, v2
	v_mov_b32_e32 v112, v2
	v_mov_b32_e32 v113, v2
	v_mov_b32_e32 v118, v2
	v_mov_b32_e32 v119, v2
	v_mov_b32_e32 v120, v2
	v_mov_b32_e32 v121, v2
	v_mov_b32_e32 v126, v2
	v_mov_b32_e32 v127, v2
	v_mov_b32_e32 v128, v2
	v_mov_b32_e32 v129, v2
	s_nop 0
	s_nop 0
	s_nop 0
	s_nop 0
	s_nop 0
	s_nop 0

.LBB0_2018:
	s_ashr_i32 s57, s56, 31
	s_lshl_b64 s[0:1], s[56:57], 19
	s_add_u32 s58, s78, s0
	s_addc_u32 s59, s79, s1
	s_and_b64 s[0:1], s[4:5], exec
	s_cselect_b32 s7, s59, s11
	s_cselect_b32 s9, s58, s10
	s_ashr_i32 s55, s54, 31
	s_lshl_b64 s[0:1], s[54:55], 19
	s_add_u32 s60, s33, s0
	s_addc_u32 s61, s64, s1
	s_and_b64 s[0:1], s[4:5], exec
	s_cselect_b32 s55, s61, s3
	s_cselect_b32 s57, s60, s2
	s_add_u32 s10, s10, 0x40080
	s_addc_u32 s11, s11, 0
	s_add_u32 s62, s2, 0x100
	v_mov_b32_e32 v2, 0
	s_addc_u32 s63, s3, 0
	s_mov_b32 s77, -2
	v_mov_b32_e32 v3, v2
	v_mov_b32_e32 v4, v2
	v_mov_b32_e32 v5, v2
	v_mov_b32_e32 v6, v2
	v_mov_b32_e32 v7, v2
	v_mov_b32_e32 v8, v2
	v_mov_b32_e32 v9, v2
	v_mov_b32_e32 v10, v2
	v_mov_b32_e32 v11, v2
	v_mov_b32_e32 v12, v2
	v_mov_b32_e32 v13, v2
	v_mov_b32_e32 v14, v2
	v_mov_b32_e32 v15, v2
	v_mov_b32_e32 v16, v2
	v_mov_b32_e32 v17, v2
	v_mov_b32_e32 v18, v2
	v_mov_b32_e32 v19, v2
	v_mov_b32_e32 v20, v2
	v_mov_b32_e32 v21, v2
	v_mov_b32_e32 v22, v2
	v_mov_b32_e32 v23, v2
	v_mov_b32_e32 v24, v2
	v_mov_b32_e32 v25, v2
	v_mov_b32_e32 v26, v2
	v_mov_b32_e32 v27, v2
	v_mov_b32_e32 v28, v2
	v_mov_b32_e32 v29, v2
	v_mov_b32_e32 v30, v2
	v_mov_b32_e32 v31, v2
	v_mov_b32_e32 v32, v2
	v_mov_b32_e32 v33, v2
	v_mov_b32_e32 v66, v2
	v_mov_b32_e32 v67, v2
	v_mov_b32_e32 v68, v2
	v_mov_b32_e32 v69, v2
	v_mov_b32_e32 v70, v2
	v_mov_b32_e32 v71, v2
	v_mov_b32_e32 v72, v2
	v_mov_b32_e32 v73, v2
	v_mov_b32_e32 v74, v2
	v_mov_b32_e32 v75, v2
	v_mov_b32_e32 v76, v2
	v_mov_b32_e32 v77, v2
	v_mov_b32_e32 v78, v2
	v_mov_b32_e32 v79, v2
	v_mov_b32_e32 v80, v2
	v_mov_b32_e32 v81, v2
	v_mov_b32_e32 v82, v2
	v_mov_b32_e32 v83, v2
	v_mov_b32_e32 v84, v2
	v_mov_b32_e32 v85, v2
	v_mov_b32_e32 v86, v2
	v_mov_b32_e32 v87, v2
	v_mov_b32_e32 v88, v2
	v_mov_b32_e32 v89, v2
	v_mov_b32_e32 v90, v2
	v_mov_b32_e32 v91, v2
	v_mov_b32_e32 v92, v2
	v_mov_b32_e32 v93, v2
	v_mov_b32_e32 v94, v2
	v_mov_b32_e32 v95, v2
	v_mov_b32_e32 v96, v2
	v_mov_b32_e32 v97, v2
	v_mov_b32_e32 v34, v2
	v_mov_b32_e32 v35, v2
	v_mov_b32_e32 v36, v2
	v_mov_b32_e32 v37, v2
	v_mov_b32_e32 v38, v2
	v_mov_b32_e32 v39, v2
	v_mov_b32_e32 v40, v2
	v_mov_b32_e32 v41, v2
	v_mov_b32_e32 v42, v2
	v_mov_b32_e32 v43, v2
	v_mov_b32_e32 v44, v2
	v_mov_b32_e32 v45, v2
	v_mov_b32_e32 v46, v2
	v_mov_b32_e32 v47, v2
	v_mov_b32_e32 v48, v2
	v_mov_b32_e32 v49, v2
	v_mov_b32_e32 v50, v2
	v_mov_b32_e32 v51, v2
	v_mov_b32_e32 v52, v2
	v_mov_b32_e32 v53, v2
	v_mov_b32_e32 v54, v2
	v_mov_b32_e32 v55, v2
	v_mov_b32_e32 v56, v2
	v_mov_b32_e32 v57, v2
	v_mov_b32_e32 v58, v2
	v_mov_b32_e32 v59, v2
	v_mov_b32_e32 v60, v2
	v_mov_b32_e32 v61, v2
	v_mov_b32_e32 v62, v2
	v_mov_b32_e32 v63, v2
	v_mov_b32_e32 v64, v2
	v_mov_b32_e32 v65, v2
	v_mov_b32_e32 v98, v2
	v_mov_b32_e32 v99, v2
	v_mov_b32_e32 v100, v2
	v_mov_b32_e32 v101, v2
	v_mov_b32_e32 v102, v2
	v_mov_b32_e32 v103, v2
	v_mov_b32_e32 v104, v2
	v_mov_b32_e32 v105, v2
	v_mov_b32_e32 v106, v2
	v_mov_b32_e32 v107, v2
	v_mov_b32_e32 v108, v2
	v_mov_b32_e32 v109, v2
	v_mov_b32_e32 v118, v2
	v_mov_b32_e32 v119, v2
	v_mov_b32_e32 v120, v2
	v_mov_b32_e32 v121, v2
	v_mov_b32_e32 v130, v2
	v_mov_b32_e32 v131, v2
	v_mov_b32_e32 v132, v2
	v_mov_b32_e32 v133, v2
	v_mov_b32_e32 v134, v2
	v_mov_b32_e32 v135, v2
	v_mov_b32_e32 v136, v2
	v_mov_b32_e32 v137, v2
	v_mov_b32_e32 v138, v2
	v_mov_b32_e32 v139, v2
	v_mov_b32_e32 v140, v2
	v_mov_b32_e32 v141, v2
	v_mov_b32_e32 v142, v2
	v_mov_b32_e32 v143, v2
	v_mov_b32_e32 v144, v2
	v_mov_b32_e32 v145, v2
	s_nop 0

.LBB0_2117:
	s_ashr_i32 s29, s28, 31
	s_lshl_b64 s[0:1], s[28:29], 19
	s_add_u32 s30, s33, s0
	s_addc_u32 s31, s42, s1
	s_and_b64 s[0:1], s[6:7], exec
	s_cselect_b32 s11, s31, s39
	s_cselect_b32 s29, s30, s38
	s_ashr_i32 s27, s26, 31
	s_lshl_b64 s[0:1], s[26:27], 19
	s_add_u32 s34, s43, s0
	s_addc_u32 s35, s44, s1
	s_and_b64 s[0:1], s[6:7], exec
	s_cselect_b32 s27, s35, s3
	s_cselect_b32 s56, s34, s2
	s_add_u32 s38, s38, 0x40080
	s_addc_u32 s39, s39, 0
	s_add_u32 s57, s2, 0x100
	v_mov_b32_e32 v2, 0
	s_addc_u32 s58, s3, 0
	s_mov_b32 s59, -2
	s_waitcnt lgkmcnt(0)
	v_mov_b32_e32 v3, v2
	v_mov_b32_e32 v4, v2
	v_mov_b32_e32 v5, v2
	v_mov_b32_e32 v6, v2
	v_mov_b32_e32 v7, v2
	v_mov_b32_e32 v8, v2
	v_mov_b32_e32 v9, v2
	v_mov_b32_e32 v18, v2
	v_mov_b32_e32 v19, v2
	v_mov_b32_e32 v20, v2
	v_mov_b32_e32 v21, v2
	v_mov_b32_e32 v22, v2
	v_mov_b32_e32 v23, v2
	v_mov_b32_e32 v24, v2
	v_mov_b32_e32 v25, v2
	v_mov_b32_e32 v34, v2
	v_mov_b32_e32 v35, v2
	v_mov_b32_e32 v36, v2
	v_mov_b32_e32 v37, v2
	v_mov_b32_e32 v38, v2
	v_mov_b32_e32 v39, v2
	v_mov_b32_e32 v40, v2
	v_mov_b32_e32 v41, v2
	v_mov_b32_e32 v50, v2
	v_mov_b32_e32 v51, v2
	v_mov_b32_e32 v52, v2
	v_mov_b32_e32 v53, v2
	v_mov_b32_e32 v54, v2
	v_mov_b32_e32 v55, v2
	v_mov_b32_e32 v56, v2
	v_mov_b32_e32 v57, v2
	v_mov_b32_e32 v10, v2
	v_mov_b32_e32 v11, v2
	v_mov_b32_e32 v12, v2
	v_mov_b32_e32 v13, v2
	v_mov_b32_e32 v14, v2
	v_mov_b32_e32 v15, v2
	v_mov_b32_e32 v16, v2
	v_mov_b32_e32 v17, v2
	v_mov_b32_e32 v26, v2
	v_mov_b32_e32 v27, v2
	v_mov_b32_e32 v28, v2
	v_mov_b32_e32 v29, v2
	v_mov_b32_e32 v30, v2
	v_mov_b32_e32 v31, v2
	v_mov_b32_e32 v32, v2
	v_mov_b32_e32 v33, v2
	v_mov_b32_e32 v42, v2
	v_mov_b32_e32 v43, v2
	v_mov_b32_e32 v44, v2
	v_mov_b32_e32 v45, v2
	v_mov_b32_e32 v46, v2
	v_mov_b32_e32 v47, v2
	v_mov_b32_e32 v48, v2
	v_mov_b32_e32 v49, v2
	v_mov_b32_e32 v58, v2
	v_mov_b32_e32 v59, v2
	v_mov_b32_e32 v60, v2
	v_mov_b32_e32 v61, v2
	v_mov_b32_e32 v62, v2
	v_mov_b32_e32 v63, v2
	v_mov_b32_e32 v64, v2
	v_mov_b32_e32 v65, v2
	v_mov_b32_e32 v66, v2
	v_mov_b32_e32 v67, v2
	v_mov_b32_e32 v68, v2
	v_mov_b32_e32 v69, v2
	v_mov_b32_e32 v70, v2
	v_mov_b32_e32 v71, v2
	v_mov_b32_e32 v72, v2
	v_mov_b32_e32 v73, v2
	v_mov_b32_e32 v82, v2
	v_mov_b32_e32 v83, v2
	v_mov_b32_e32 v84, v2
	v_mov_b32_e32 v85, v2
	v_mov_b32_e32 v86, v2
	v_mov_b32_e32 v87, v2
	v_mov_b32_e32 v88, v2
	v_mov_b32_e32 v89, v2
	v_mov_b32_e32 v98, v2
	v_mov_b32_e32 v99, v2
	v_mov_b32_e32 v100, v2
	v_mov_b32_e32 v101, v2
	v_mov_b32_e32 v102, v2
	v_mov_b32_e32 v103, v2
	v_mov_b32_e32 v104, v2
	v_mov_b32_e32 v105, v2
	v_mov_b32_e32 v114, v2
	v_mov_b32_e32 v115, v2
	v_mov_b32_e32 v116, v2
	v_mov_b32_e32 v117, v2
	v_mov_b32_e32 v118, v2
	v_mov_b32_e32 v119, v2
	v_mov_b32_e32 v120, v2
	v_mov_b32_e32 v121, v2
	v_mov_b32_e32 v74, v2
	v_mov_b32_e32 v75, v2
	v_mov_b32_e32 v76, v2
	v_mov_b32_e32 v77, v2
	v_mov_b32_e32 v78, v2
	v_mov_b32_e32 v79, v2
	v_mov_b32_e32 v80, v2
	v_mov_b32_e32 v81, v2
	v_mov_b32_e32 v90, v2
	v_mov_b32_e32 v91, v2
	v_mov_b32_e32 v92, v2
	v_mov_b32_e32 v93, v2
	v_mov_b32_e32 v94, v2
	v_mov_b32_e32 v95, v2
	v_mov_b32_e32 v96, v2
	v_mov_b32_e32 v97, v2
	v_mov_b32_e32 v106, v2
	v_mov_b32_e32 v107, v2
	v_mov_b32_e32 v108, v2
	v_mov_b32_e32 v109, v2
	v_mov_b32_e32 v110, v2
	v_mov_b32_e32 v111, v2
	v_mov_b32_e32 v112, v2
	v_mov_b32_e32 v113, v2
	v_mov_b32_e32 v122, v2
	v_mov_b32_e32 v123, v2
	v_mov_b32_e32 v124, v2
	v_mov_b32_e32 v125, v2
	v_mov_b32_e32 v126, v2
	v_mov_b32_e32 v127, v2
	v_mov_b32_e32 v128, v2
	v_mov_b32_e32 v129, v2
	s_nop 0
	s_nop 0
	s_nop 0
	s_nop 0
	s_nop 0
	s_nop 0
	s_nop 0

.LBB0_2289:
	s_add_u32 s16, s16, 0xb0080
	s_addc_u32 s17, s17, 0
	s_add_u32 s41, s2, 0x100
	v_mov_b32_e32 v0, 0
	s_addc_u32 s42, s3, 0
	s_mov_b32 s43, -2
	v_mov_b32_e32 v1, v0
	v_mov_b32_e32 v2, v0
	v_mov_b32_e32 v3, v0
	v_mov_b32_e32 v4, v0
	v_mov_b32_e32 v5, v0
	v_mov_b32_e32 v6, v0
	v_mov_b32_e32 v7, v0
	v_mov_b32_e32 v12, v0
	v_mov_b32_e32 v13, v0
	v_mov_b32_e32 v14, v0
	v_mov_b32_e32 v15, v0
	v_mov_b32_e32 v20, v0
	v_mov_b32_e32 v21, v0
	v_mov_b32_e32 v22, v0
	v_mov_b32_e32 v23, v0
	v_mov_b32_e32 v28, v0
	v_mov_b32_e32 v29, v0
	v_mov_b32_e32 v30, v0
	v_mov_b32_e32 v31, v0
	v_mov_b32_e32 v36, v0
	v_mov_b32_e32 v37, v0
	v_mov_b32_e32 v38, v0
	v_mov_b32_e32 v39, v0
	v_mov_b32_e32 v44, v0
	v_mov_b32_e32 v45, v0
	v_mov_b32_e32 v46, v0
	v_mov_b32_e32 v47, v0
	v_mov_b32_e32 v52, v0
	v_mov_b32_e32 v53, v0
	v_mov_b32_e32 v54, v0
	v_mov_b32_e32 v55, v0
	v_mov_b32_e32 v8, v0
	v_mov_b32_e32 v9, v0
	v_mov_b32_e32 v10, v0
	v_mov_b32_e32 v11, v0
	v_mov_b32_e32 v16, v0
	v_mov_b32_e32 v17, v0
	v_mov_b32_e32 v18, v0
	v_mov_b32_e32 v19, v0
	v_mov_b32_e32 v24, v0
	v_mov_b32_e32 v25, v0
	v_mov_b32_e32 v26, v0
	v_mov_b32_e32 v27, v0
	v_mov_b32_e32 v32, v0
	v_mov_b32_e32 v33, v0
	v_mov_b32_e32 v34, v0
	v_mov_b32_e32 v35, v0
	v_mov_b32_e32 v40, v0
	v_mov_b32_e32 v41, v0
	v_mov_b32_e32 v42, v0
	v_mov_b32_e32 v43, v0
	v_mov_b32_e32 v48, v0
	v_mov_b32_e32 v49, v0
	v_mov_b32_e32 v50, v0
	v_mov_b32_e32 v51, v0
	v_mov_b32_e32 v56, v0
	v_mov_b32_e32 v57, v0
	v_mov_b32_e32 v58, v0
	v_mov_b32_e32 v59, v0
	v_mov_b32_e32 v60, v0
	v_mov_b32_e32 v61, v0
	v_mov_b32_e32 v62, v0
	v_mov_b32_e32 v63, v0
	v_mov_b32_e32 v64, v0
	v_mov_b32_e32 v65, v0
	v_mov_b32_e32 v66, v0
	v_mov_b32_e32 v67, v0
	v_mov_b32_e32 v68, v0
	v_mov_b32_e32 v69, v0
	v_mov_b32_e32 v70, v0
	v_mov_b32_e32 v71, v0
	v_mov_b32_e32 v76, v0
	v_mov_b32_e32 v77, v0
	v_mov_b32_e32 v78, v0
	v_mov_b32_e32 v79, v0
	v_mov_b32_e32 v84, v0
	v_mov_b32_e32 v85, v0
	v_mov_b32_e32 v86, v0
	v_mov_b32_e32 v87, v0
	v_mov_b32_e32 v92, v0
	v_mov_b32_e32 v93, v0
	v_mov_b32_e32 v94, v0
	v_mov_b32_e32 v95, v0
	v_mov_b32_e32 v100, v0
	v_mov_b32_e32 v101, v0
	v_mov_b32_e32 v102, v0
	v_mov_b32_e32 v103, v0
	v_mov_b32_e32 v108, v0
	v_mov_b32_e32 v109, v0
	v_mov_b32_e32 v110, v0
	v_mov_b32_e32 v111, v0
	v_mov_b32_e32 v116, v0
	v_mov_b32_e32 v117, v0
	v_mov_b32_e32 v118, v0
	v_mov_b32_e32 v119, v0
	v_mov_b32_e32 v72, v0
	v_mov_b32_e32 v73, v0
	v_mov_b32_e32 v74, v0
	v_mov_b32_e32 v75, v0
	v_mov_b32_e32 v80, v0
	v_mov_b32_e32 v81, v0
	v_mov_b32_e32 v82, v0
	v_mov_b32_e32 v83, v0
	v_mov_b32_e32 v88, v0
	v_mov_b32_e32 v89, v0
	v_mov_b32_e32 v90, v0
	v_mov_b32_e32 v91, v0
	v_mov_b32_e32 v96, v0
	v_mov_b32_e32 v97, v0
	v_mov_b32_e32 v98, v0
	v_mov_b32_e32 v99, v0
	v_mov_b32_e32 v104, v0
	v_mov_b32_e32 v105, v0
	v_mov_b32_e32 v106, v0
	v_mov_b32_e32 v107, v0
	v_mov_b32_e32 v112, v0
	v_mov_b32_e32 v113, v0
	v_mov_b32_e32 v114, v0
	v_mov_b32_e32 v115, v0
	v_mov_b32_e32 v120, v0
	v_mov_b32_e32 v121, v0
	v_mov_b32_e32 v122, v0
	v_mov_b32_e32 v123, v0
	v_mov_b32_e32 v124, v0
	v_mov_b32_e32 v125, v0
	v_mov_b32_e32 v126, v0
	v_mov_b32_e32 v127, v0
	s_nop 0
	s_nop 0
	s_nop 0
	s_nop 0
	s_nop 0
	s_nop 0
	s_nop 0
	s_nop 0
	s_nop 0
	s_nop 0
	s_nop 0
